# attention tile loop: K-fragment LDS reads hoisted to loop top; prefetched K/V tile LDS stores moved ahead of the last four PV MFMAs
# speedup vs baseline: 1.0281x; 1.0069x over previous
.LBB0_506:
	s_bitcmp1_b32 s25, 0
	s_cselect_b32 s49, 0x9400, 0
	v_add3_u32 v0, s49, v249, v248
	v_add_u32_e32 v240, s49, v245
	ds_read_b128 v[142:145], v0
	ds_read_b128 v[146:149], v0 offset:32
	ds_read_b128 v[150:153], v0 offset:64
	ds_read_b128 v[154:157], v0 offset:96
	ds_read_b128 v[2:5], v0 offset:8704
	ds_read_b128 v[6:9], v0 offset:8736
	ds_read_b128 v[10:13], v0 offset:8768
	ds_read_b128 v[208:211], v0 offset:8800
	v_add3_u32 v240, v240, v246, v247
	s_add_i32 s48, s70, 1
	s_cmp_gt_i32 s48, s22
	s_cselect_b64 s[20:21], -1, 0
	s_cmp_le_i32 s48, s22
	s_cbranch_scc1 .LBB0_509
	s_lshl_b64 s[50:51], s[70:71], 6
	s_add_u32 s50, s50, s44
	s_addc_u32 s51, s51, 0
	s_lshl_b64 s[50:51], s[50:51], 11
	v_readlane_b32 s101, v229, 0
	s_add_u32 s50, s50, s40
	s_addc_u32 s51, s51, s41
	s_add_u32 s50, s50, s101
	s_addc_u32 s51, s51, 0
	global_load_dwordx4 v[190:193], v232, s[50:51]
	global_load_dwordx4 v[198:201], v234, s[50:51]
	s_add_u32 s50, s50, 0x8000000
	s_addc_u32 s51, s51, 0
	global_load_dwordx4 v[194:197], v232, s[50:51]
	global_load_dwordx4 v[202:205], v234, s[50:51]
	s_cmp_gt_i32 s48, s24
	s_cbranch_scc0 .LBB0_510

.LBB0_510:
	s_add_i32 s49, s63, s25
	s_cmp_lg_u32 s49, 0
	s_waitcnt lgkmcnt(7)
	v_mfma_f32_32x32x16_bf16 v[158:173], v[142:145], v[174:177], v[80:95]
	s_waitcnt lgkmcnt(6)
	v_mfma_f32_32x32x16_bf16 v[158:173], v[146:149], v[178:181], v[158:173]
	s_waitcnt lgkmcnt(5)
	v_mfma_f32_32x32x16_bf16 v[158:173], v[150:153], v[182:185], v[158:173]
	s_waitcnt lgkmcnt(4)
	v_mfma_f32_32x32x16_bf16 v[158:173], v[154:157], v[186:189], v[158:173]
	s_waitcnt lgkmcnt(3)
	v_mfma_f32_32x32x16_bf16 v[142:157], v[2:5], v[174:177], v[96:111]
	s_waitcnt lgkmcnt(2)
	v_mfma_f32_32x32x16_bf16 v[142:157], v[6:9], v[178:181], v[142:157]
	s_waitcnt lgkmcnt(1)
	v_mfma_f32_32x32x16_bf16 v[142:157], v[10:13], v[182:185], v[142:157]
	s_waitcnt lgkmcnt(0)
	v_mfma_f32_32x32x16_bf16 v[142:157], v[208:211], v[186:189], v[142:157]
	ds_read_b64_tr_b16 v[2:3], v240 offset:17408
	ds_read_b64_tr_b16 v[4:5], v240 offset:19968
	ds_read_b64_tr_b16 v[6:7], v240 offset:17472
	ds_read_b64_tr_b16 v[8:9], v240 offset:20032
	ds_read_b64_tr_b16 v[10:11], v240 offset:17536
	ds_read_b64_tr_b16 v[12:13], v240 offset:20096
	ds_read_b64_tr_b16 v[208:209], v240 offset:17600
	ds_read_b64_tr_b16 v[210:211], v240 offset:20160
	ds_read_b64_tr_b16 v[212:213], v240 offset:22528
	ds_read_b64_tr_b16 v[214:215], v240 offset:25088
	s_cbranch_scc0 .LBB0_512
	v_cvt_f32_i32_e32 v0, s49
	v_fmamk_f32 v0, v0, 0x42800000, v244
	v_mul_f32_e64 v0, v0, -v226
	s_cmp_eq_u32 s100, 0
	s_cbranch_scc1 .LBB0_515
	s_branch .LBB0_513

.LBB0_515:
	v_sub_f32_e32 v0, v251, v0
	v_sub_f32_e32 v158, v158, v0
	v_sub_f32_e32 v159, v159, v0
	v_exp_f32_e32 v158, v158
	v_exp_f32_e32 v159, v159
	v_add_f32_e32 v14, 0, v158
	v_add_f32_e32 v14, v159, v14
	v_cvt_pk_bf16_f32 v158, v158, v159
	v_sub_f32_e32 v160, v160, v0
	v_sub_f32_e32 v161, v161, v0
	v_exp_f32_e32 v160, v160
	v_exp_f32_e32 v161, v161
	v_add_f32_e32 v14, v160, v14
	v_add_f32_e32 v14, v161, v14
	v_cvt_pk_bf16_f32 v159, v160, v161
	v_sub_f32_e32 v162, v162, v0
	v_sub_f32_e32 v163, v163, v0
	v_exp_f32_e32 v162, v162
	v_exp_f32_e32 v163, v163
	v_add_f32_e32 v14, v162, v14
	v_add_f32_e32 v14, v163, v14
	v_cvt_pk_bf16_f32 v160, v162, v163
	v_sub_f32_e32 v164, v164, v0
	v_sub_f32_e32 v165, v165, v0
	v_exp_f32_e32 v164, v164
	v_exp_f32_e32 v165, v165
	v_add_f32_e32 v14, v164, v14
	v_add_f32_e32 v14, v165, v14
	v_cvt_pk_bf16_f32 v161, v164, v165
	ds_read_b64_tr_b16 v[162:163], v240 offset:22592
	ds_read_b64_tr_b16 v[164:165], v240 offset:25152
	s_waitcnt lgkmcnt(10)
	v_mfma_f32_32x32x16_bf16 v[64:79], v[2:5], v[158:161], v[64:79]
	ds_read_b64_tr_b16 v[2:3], v240 offset:22656
	ds_read_b64_tr_b16 v[4:5], v240 offset:25216
	v_sub_f32_e32 v166, v166, v0
	v_sub_f32_e32 v167, v167, v0
	v_exp_f32_e32 v166, v166
	v_exp_f32_e32 v167, v167
	v_add_f32_e32 v14, v166, v14
	v_add_f32_e32 v14, v167, v14
	v_cvt_pk_bf16_f32 v166, v166, v167
	s_waitcnt lgkmcnt(10)
	v_mfma_f32_32x32x16_bf16 v[48:63], v[6:9], v[158:161], v[48:63]
	ds_read_b64_tr_b16 v[6:7], v240 offset:22720
	ds_read_b64_tr_b16 v[8:9], v240 offset:25280
	v_sub_f32_e32 v168, v168, v0
	v_sub_f32_e32 v169, v169, v0
	v_exp_f32_e32 v168, v168
	v_exp_f32_e32 v169, v169
	v_add_f32_e32 v14, v168, v14
	v_add_f32_e32 v14, v169, v14
	v_cvt_pk_bf16_f32 v167, v168, v169
	s_waitcnt lgkmcnt(10)
	v_mfma_f32_32x32x16_bf16 v[32:47], v[10:13], v[158:161], v[32:47]
	ds_read_b64_tr_b16 v[10:11], v240 offset:27648
	ds_read_b64_tr_b16 v[12:13], v240 offset:30208
	v_sub_f32_e32 v170, v170, v0
	v_sub_f32_e32 v171, v171, v0
	v_exp_f32_e32 v170, v170
	v_exp_f32_e32 v171, v171
	v_add_f32_e32 v14, v170, v14
	v_add_f32_e32 v14, v171, v14
	v_cvt_pk_bf16_f32 v168, v170, v171
	s_waitcnt lgkmcnt(10)
	v_mfma_f32_32x32x16_bf16 v[16:31], v[208:211], v[158:161], v[16:31]
	ds_read_b64_tr_b16 v[208:209], v240 offset:27712
	ds_read_b64_tr_b16 v[210:211], v240 offset:30272
	v_sub_f32_e32 v172, v172, v0
	v_sub_f32_e32 v173, v173, v0
	v_exp_f32_e32 v172, v172
	v_exp_f32_e32 v173, v173
	v_add_f32_e32 v14, v172, v14
	v_add_f32_e32 v14, v173, v14
	v_cvt_pk_bf16_f32 v169, v172, v173
	ds_read_b64_tr_b16 v[170:171], v240 offset:27776
	ds_read_b64_tr_b16 v[172:173], v240 offset:30336
	s_waitcnt lgkmcnt(12)
	v_mfma_f32_32x32x16_bf16 v[64:79], v[212:215], v[166:169], v[64:79]
	ds_read_b64_tr_b16 v[212:213], v240 offset:27840
	ds_read_b64_tr_b16 v[214:215], v240 offset:30400
	v_sub_f32_e32 v142, v142, v0
	v_sub_f32_e32 v143, v143, v0
	v_exp_f32_e32 v142, v142
	v_exp_f32_e32 v143, v143
	v_add_f32_e32 v14, v142, v14
	v_add_f32_e32 v14, v143, v14
	v_cvt_pk_bf16_f32 v142, v142, v143
	s_waitcnt lgkmcnt(12)
	v_mfma_f32_32x32x16_bf16 v[48:63], v[162:165], v[166:169], v[48:63]
	ds_read_b64_tr_b16 v[162:163], v240 offset:32768
	ds_read_b64_tr_b16 v[164:165], v240 offset:35328
	v_sub_f32_e32 v144, v144, v0
	v_sub_f32_e32 v145, v145, v0
	v_exp_f32_e32 v144, v144
	v_exp_f32_e32 v145, v145
	v_add_f32_e32 v14, v144, v14
	v_add_f32_e32 v14, v145, v14
	v_cvt_pk_bf16_f32 v143, v144, v145
	s_waitcnt lgkmcnt(12)
	v_mfma_f32_32x32x16_bf16 v[32:47], v[2:5], v[166:169], v[32:47]
	ds_read_b64_tr_b16 v[2:3], v240 offset:32832
	ds_read_b64_tr_b16 v[4:5], v240 offset:35392
	v_sub_f32_e32 v146, v146, v0
	v_sub_f32_e32 v147, v147, v0
	v_exp_f32_e32 v146, v146
	v_exp_f32_e32 v147, v147
	v_add_f32_e32 v14, v146, v14
	v_add_f32_e32 v14, v147, v14
	v_cvt_pk_bf16_f32 v144, v146, v147
	s_waitcnt lgkmcnt(12)
	v_mfma_f32_32x32x16_bf16 v[16:31], v[6:9], v[166:169], v[16:31]
	ds_read_b64_tr_b16 v[6:7], v240 offset:32896
	ds_read_b64_tr_b16 v[8:9], v240 offset:35456
	v_sub_f32_e32 v148, v148, v0
	v_sub_f32_e32 v149, v149, v0
	v_exp_f32_e32 v148, v148
	v_exp_f32_e32 v149, v149
	v_add_f32_e32 v14, v148, v14
	v_add_f32_e32 v14, v149, v14
	v_cvt_pk_bf16_f32 v145, v148, v149
	ds_read_b64_tr_b16 v[146:147], v240 offset:32960
	ds_read_b64_tr_b16 v[148:149], v240 offset:35520
	s_waitcnt lgkmcnt(14)
	v_mfma_f32_32x32x16_bf16 v[64:79], v[10:13], v[142:145], v[64:79]
	v_sub_f32_e32 v150, v150, v0
	v_sub_f32_e32 v151, v151, v0
	v_exp_f32_e32 v150, v150
	v_exp_f32_e32 v151, v151
	v_add_f32_e32 v14, v150, v14
	v_add_f32_e32 v14, v151, v14
	v_cvt_pk_bf16_f32 v150, v150, v151
	s_waitcnt lgkmcnt(12)
	v_mfma_f32_32x32x16_bf16 v[48:63], v[208:211], v[142:145], v[48:63]
	v_sub_f32_e32 v152, v152, v0
	v_sub_f32_e32 v153, v153, v0
	v_exp_f32_e32 v152, v152
	v_exp_f32_e32 v153, v153
	v_add_f32_e32 v14, v152, v14
	v_add_f32_e32 v14, v153, v14
	v_cvt_pk_bf16_f32 v151, v152, v153
	s_waitcnt lgkmcnt(10)
	v_mfma_f32_32x32x16_bf16 v[32:47], v[170:173], v[142:145], v[32:47]
	v_sub_f32_e32 v154, v154, v0
	v_sub_f32_e32 v155, v155, v0
	v_exp_f32_e32 v154, v154
	v_exp_f32_e32 v155, v155
	v_add_f32_e32 v14, v154, v14
	v_add_f32_e32 v14, v155, v14
	v_cvt_pk_bf16_f32 v152, v154, v155
	s_waitcnt lgkmcnt(8)
	v_mfma_f32_32x32x16_bf16 v[16:31], v[212:215], v[142:145], v[16:31]
	v_sub_f32_e32 v156, v156, v0
	v_sub_f32_e32 v157, v157, v0
	v_exp_f32_e32 v156, v156
	v_exp_f32_e32 v157, v157
	v_add_f32_e32 v14, v156, v14
	v_add_f32_e32 v14, v157, v14
	v_cvt_pk_bf16_f32 v153, v156, v157
	v_add_f32_e32 v250, v250, v14
	s_andn2_b64 vcc, exec, s[20:21]
	s_cbranch_vccnz .Lattn_pv3_nostore
	s_andn2_b32 s101, 1, s25
	s_mul_i32 s101, s101, 0x9400
	v_add_u32_e32 v14, s101, v221
	v_add_u32_e32 v15, v14, v242
	v_add_u32_e32 v239, v14, v241
	v_add_u32_e32 v252, v14, v225
	v_add_u32_e32 v14, v14, v223
	s_waitcnt vmcnt(3)
	ds_write_b128 v14, v[190:193]
	s_waitcnt vmcnt(2)
	ds_write_b128 v239, v[198:201]
	s_waitcnt vmcnt(1)
	ds_write_b128 v252, v[194:197] offset:17408
	s_waitcnt vmcnt(0)
	ds_write_b128 v15, v[202:205] offset:17408
	s_waitcnt lgkmcnt(10)
	v_mfma_f32_32x32x16_bf16 v[64:79], v[162:165], v[150:153], v[64:79]
	s_waitcnt lgkmcnt(8)
	v_mfma_f32_32x32x16_bf16 v[48:63], v[2:5], v[150:153], v[48:63]
	s_waitcnt lgkmcnt(6)
	v_mfma_f32_32x32x16_bf16 v[32:47], v[6:9], v[150:153], v[32:47]
	s_waitcnt lgkmcnt(4)
	v_mfma_f32_32x32x16_bf16 v[16:31], v[146:149], v[150:153], v[16:31]
	s_branch .LBB0_505
.Lattn_pv3_nostore:
	s_waitcnt lgkmcnt(6)
	v_mfma_f32_32x32x16_bf16 v[64:79], v[162:165], v[150:153], v[64:79]
	s_waitcnt lgkmcnt(4)
	v_mfma_f32_32x32x16_bf16 v[48:63], v[2:5], v[150:153], v[48:63]
	s_waitcnt lgkmcnt(2)
	v_mfma_f32_32x32x16_bf16 v[32:47], v[6:9], v[150:153], v[32:47]
	s_waitcnt lgkmcnt(0)
	v_mfma_f32_32x32x16_bf16 v[16:31], v[146:149], v[150:153], v[16:31]
	s_branch .LBB0_505
.LBB0_516:
	s_andn2_b32 s20, 1, s25
	s_mul_i32 s20, s20, 0x9400
	v_add_u32_e32 v14, s20, v221
	v_add_u32_e32 v15, v14, v242
	v_add_u32_e32 v239, v14, v241
	v_add_u32_e32 v252, v14, v225
	v_add_u32_e32 v14, v14, v223
	s_waitcnt vmcnt(3)
	ds_write_b128 v14, v[190:193]
	s_waitcnt vmcnt(2)
	ds_write_b128 v239, v[198:201]
	s_waitcnt vmcnt(1)
	ds_write_b128 v252, v[194:197] offset:17408
	s_waitcnt vmcnt(0)
	ds_write_b128 v15, v[202:205] offset:17408
	s_branch .LBB0_505
